# in-phase grid barriers of the fused RMS/LayerNorm GEMM epilogues: dropped the L2 writeback + invalidate (only the sc1 row statistics cross workgroups there)
# speedup vs baseline: 1.0039x; 1.0039x over previous
.LBB0_452:
	s_or_b64 exec, exec, s[4:5]
	s_waitcnt vmcnt(0)
	s_waitcnt vmcnt(0)
.LBB0_453:
	s_andn2_saveexec_b64 s[0:1], s[0:1]
	s_cbranch_execz .LBB0_471
	s_mov_b64 s[0:1], exec
	s_waitcnt lgkmcnt(0)
	s_waitcnt vmcnt(0)
	v_mbcnt_lo_u32_b32 v131, s0, 0
	v_mbcnt_hi_u32_b32 v131, s1, v131
	v_cmp_eq_u32_e32 vcc, 0, v131
	s_and_saveexec_b64 s[4:5], vcc
	s_cbranch_execz .LBB0_456
	s_bcnt1_i32_b64 s0, s[0:1]
	v_mov_b32_e32 v133, 0
	v_mov_b32_e32 v134, s0
	global_atomic_add v133, v133, v134, s[54:55] sc0

.LBB0_470:
	s_or_b64 exec, exec, s[0:1]
	v_mov_b32_e32 v130, 0
	v_mov_b32_e32 v131, 1
	s_waitcnt vmcnt(0)
	global_atomic_add v130, v131, s[50:51]
	s_waitcnt vmcnt(0)

.LBB0_986:
	s_or_b64 exec, exec, s[6:7]
	s_waitcnt vmcnt(0)
	s_waitcnt vmcnt(0)
.LBB0_987:
	s_andn2_saveexec_b64 s[4:5], s[4:5]
	s_cbranch_execz .LBB0_1005
	s_mov_b64 s[4:5], exec
	s_waitcnt lgkmcnt(0)
	s_waitcnt vmcnt(0)
	v_mbcnt_lo_u32_b32 v3, s4, 0
	v_mbcnt_hi_u32_b32 v3, s5, v3
	v_cmp_eq_u32_e32 vcc, 0, v3
	s_and_saveexec_b64 s[6:7], vcc
	s_cbranch_execz .LBB0_990
	s_bcnt1_i32_b64 s4, s[4:5]
	v_mov_b32_e32 v5, s4
	global_atomic_add v5, v129, v5, s[60:61] sc0

.LBB0_1004:
	s_or_b64 exec, exec, s[4:5]
	s_waitcnt vmcnt(0)
	global_atomic_add v129, v179, s[54:55]
	s_waitcnt vmcnt(0)

.LBB0_1267:
	s_or_b64 exec, exec, s[0:1]
	s_waitcnt vmcnt(0)
	s_waitcnt vmcnt(0)
.LBB0_1268:
	s_andn2_saveexec_b64 s[0:1], s[96:97]
	s_cbranch_execz .LBB0_1286
	s_mov_b64 s[0:1], exec
	s_waitcnt lgkmcnt(0)
	s_waitcnt vmcnt(0)
	v_mbcnt_lo_u32_b32 v3, s0, 0
	v_mbcnt_hi_u32_b32 v3, s1, v3
	v_cmp_eq_u32_e32 vcc, 0, v3
	s_and_saveexec_b64 s[4:5], vcc
	s_cbranch_execz .LBB0_1271
	s_bcnt1_i32_b64 s0, s[0:1]
	v_mov_b32_e32 v5, s0
	v_readlane_b32 s0, v250, 9
	v_readlane_b32 s1, v250, 10
	s_nop 4
	global_atomic_add v5, v129, v5, s[0:1] sc0

.LBB0_1285:
	s_or_b64 exec, exec, s[0:1]
	s_waitcnt vmcnt(0)
	global_atomic_add v129, v195, s[26:27]
	s_waitcnt vmcnt(0)

.LBB0_1780:
	s_or_b64 exec, exec, s[8:9]
	s_waitcnt vmcnt(0)
	s_waitcnt vmcnt(0)
.LBB0_1781:
	s_andn2_saveexec_b64 s[6:7], s[6:7]
	s_cbranch_execz .LBB0_1799
	s_mov_b64 s[6:7], exec
	s_waitcnt lgkmcnt(0)
	s_waitcnt vmcnt(0)
	v_mbcnt_lo_u32_b32 v3, s6, 0
	v_mbcnt_hi_u32_b32 v3, s7, v3
	v_cmp_eq_u32_e32 vcc, 0, v3
	s_and_saveexec_b64 s[8:9], vcc
	s_cbranch_execz .LBB0_1784
	s_bcnt1_i32_b64 s6, s[6:7]
	v_mov_b32_e32 v5, s6
	global_atomic_add v5, v129, v5, s[60:61] sc0

.LBB0_1798:
	s_or_b64 exec, exec, s[6:7]
	s_waitcnt vmcnt(0)
	global_atomic_add v129, v195, s[54:55]
	s_waitcnt vmcnt(0)

.LBB0_2113:
	s_or_b64 exec, exec, s[96:97]
	s_waitcnt vmcnt(0)
	s_waitcnt vmcnt(0)
.LBB0_2114:
	s_andn2_saveexec_b64 s[0:1], s[94:95]
	s_cbranch_execz .LBB0_2132
	s_mov_b64 s[0:1], exec
	s_waitcnt lgkmcnt(0)
	s_waitcnt vmcnt(0)
	v_mbcnt_lo_u32_b32 v3, s0, 0
	v_mbcnt_hi_u32_b32 v3, s1, v3
	v_cmp_eq_u32_e32 vcc, 0, v3
	s_and_saveexec_b64 s[4:5], vcc
	s_cbranch_execz .LBB0_2117
	s_bcnt1_i32_b64 s0, s[0:1]
	v_mov_b32_e32 v5, s0
	global_atomic_add v5, v129, v5, s[76:77] sc0

.LBB0_2131:
	s_or_b64 exec, exec, s[4:5]
	s_waitcnt vmcnt(0)
	global_atomic_add v129, v181, s[66:67]
	s_waitcnt vmcnt(0)
